# norm phases: x rows loaded with the default cache policy instead of nt
# baseline (speedup 1.0000x reference)
; DI void phase_norm(const Params& p, int layer, int which  , int nrows) {
;     ...
;   for (int pr = gw; pr < (nrows >> 1); pr += nw) {
;     const int row = pr * 2;
;     const float* xr0 = xold_ptr(p, layer, first, row);
;     const float* xr1 = xold_ptr(p, layer, first, row + 1);
;     const int b9 = row < NLAT ? (row >> 12) : 8;
;     float4 v[2][4];
;     float ss0 = 0.f, ss1 = 0.f;
; #pragma unroll
;     for (int i = 0; i < 4; ++i) {
;       typedef float f4ld __attribute__((ext_vector_type(4)));
;       const f4ld a_ = __builtin_nontemporal_load((const f4ld*)xr0 + lane + 64 * i), b_ = __builtin_nontemporal_load((const f4ld*)xr1 + lane + 64 * i);
;       v[0][i] = make_float4(a_[0], a_[1], a_[2], a_[3]); v[1][i] = make_float4(b_[0], b_[1], b_[2], b_[3]);
;     }
;     const float* sh = mod + b9 * 6144 + (which == 0 ? 0 : 3) * 1024;
;     const float* sc = sh + 1024;
;     float4 gg[4], s4[4], h4[4];
; #pragma unroll
;     for (int i = 0; i < 4; ++i) {
;       const int col = 4 * (lane + 64 * i);
;       gg[i] = *(const float4*)(g + col); s4[i] = *(const float4*)(sc + col); h4[i] = *(const float4*)(sh + col);
;     }
; #pragma unroll
;     for (int i = 0; i < 4; ++i) {
;       ss0 += v[0][i].x * v[0][i].x + v[0][i].y * v[0][i].y + v[0][i].z * v[0][i].z + v[0][i].w * v[0][i].w;
;       ss1 += v[1][i].x * v[1][i].x + v[1][i].y * v[1][i].y + v[1][i].z * v[1][i].z + v[1][i].w * v[1][i].w;
;     }
;     ss0 = wave_sum(ss0); ss1 = wave_sum(ss1);
;     const float rstd0 = rsqrtf(ss0 * (1.0f / D) + 1e-6f), rstd1 = rsqrtf(ss1 * (1.0f / D) + 1e-6f);
.LBB0_333:
	v_cmp_gt_i32_e32 vcc, s94, v55
	v_add_u32_e32 v0, 0xffff8000, v36
	v_ashrrev_i32_e32 v37, 31, v36
	v_cndmask_b32_e32 v1, 0, v37, vcc
	v_cndmask_b32_e32 v0, v0, v36, vcc
	v_cndmask_b32_e32 v3, v71, v72, vcc
	v_cndmask_b32_e32 v2, v73, v74, vcc
	v_lshlrev_b64 v[0:1], 12, v[0:1]
	v_add_u32_e32 v48, 1, v36
	v_lshl_add_u64 v[0:1], v[2:3], 0, v[0:1]
	v_cmp_gt_i32_e32 vcc, s93, v48
	v_ashrrev_i32_e32 v2, 31, v48
	v_add_u32_e32 v3, 0xffff8001, v36
	v_cndmask_b32_e32 v49, 0, v2, vcc
	v_cndmask_b32_e32 v2, v3, v48, vcc
	v_mov_b32_e32 v3, v49
	v_cndmask_b32_e32 v5, v71, v72, vcc
	v_cndmask_b32_e32 v4, v73, v74, vcc
	v_lshlrev_b64 v[2:3], 12, v[2:3]
	v_lshl_add_u64 v[2:3], v[4:5], 0, v[2:3]
	v_lshl_add_u64 v[0:1], v[0:1], 0, v[38:39]
	v_lshl_add_u64 v[2:3], v[2:3], 0, v[38:39]
	global_load_dwordx4 v[28:31], v[0:1], off
	global_load_dwordx4 v[12:15], v[2:3], off
	global_load_dwordx4 v[24:27], v[0:1], off offset:1024
	global_load_dwordx4 v[8:11], v[2:3], off offset:1024
	global_load_dwordx4 v[20:23], v[0:1], off offset:2048
	global_load_dwordx4 v[4:7], v[2:3], off offset:2048
	global_load_dwordx4 v[16:19], v[0:1], off offset:3072
	s_nop 0
	global_load_dwordx4 v[0:3], v[2:3], off offset:3072
	v_min_i32_e32 v50, 0x4000, v55
	v_ashrrev_i32_e32 v50, 11, v50
	v_mul_i32_i24_e32 v50, 0x1800, v50
	v_ashrrev_i32_e32 v51, 31, v50
	v_lshl_add_u64 v[50:51], v[50:51], 2, s[12:13]
	v_lshl_add_u64 v[52:53], v[50:51], 0, s[80:81]
	v_lshl_add_u64 v[62:63], v[52:53], 0, v[40:41]
	v_lshl_add_u64 v[50:51], v[50:51], 0, v[40:41]
	v_lshl_add_u64 v[60:61], v[52:53], 0, v[42:43]
	v_lshl_add_u64 v[56:57], v[52:53], 0, v[44:45]
	v_lshl_add_u64 v[52:53], v[52:53], 0, v[46:47]
	s_waitcnt vmcnt(7)
	v_mov_b32_e32 v76, v29
	v_mov_b32_e32 v64, v28
	s_waitcnt vmcnt(5)
	v_mov_b32_e32 v77, v25
	v_mov_b32_e32 v65, v24
	v_pk_mul_f32 v[76:77], v[76:77], v[76:77]
	v_mov_b32_e32 v78, v13
	v_pk_fma_f32 v[64:65], v[64:65], v[64:65], v[76:77]
	v_mov_b32_e32 v76, v30
	v_mov_b32_e32 v77, v26
	v_pk_fma_f32 v[64:65], v[76:77], v[76:77], v[64:65]
	v_mov_b32_e32 v76, v31
	v_mov_b32_e32 v77, v27
	s_waitcnt vmcnt(4)
	v_mov_b32_e32 v79, v9
	v_pk_fma_f32 v[64:65], v[76:77], v[76:77], v[64:65]
	v_mov_b32_e32 v76, v12
	v_mov_b32_e32 v77, v8
	v_pk_mul_f32 v[78:79], v[78:79], v[78:79]
	s_waitcnt vmcnt(3)
	v_mov_b32_e32 v80, v21
	v_pk_fma_f32 v[76:77], v[76:77], v[76:77], v[78:79]
	v_mov_b32_e32 v78, v14
	v_mov_b32_e32 v79, v10
	v_pk_fma_f32 v[76:77], v[78:79], v[78:79], v[76:77]
	v_mov_b32_e32 v78, v15
	v_mov_b32_e32 v79, v11
	s_waitcnt vmcnt(1)
	v_mov_b32_e32 v81, v17
	v_pk_fma_f32 v[76:77], v[78:79], v[78:79], v[76:77]
	v_mov_b32_e32 v78, v20
	v_mov_b32_e32 v79, v16
	v_pk_mul_f32 v[80:81], v[80:81], v[80:81]
	v_mov_b32_e32 v82, v5
	v_pk_fma_f32 v[78:79], v[78:79], v[78:79], v[80:81]
	v_mov_b32_e32 v80, v22
	v_mov_b32_e32 v81, v18
	v_pk_fma_f32 v[78:79], v[80:81], v[80:81], v[78:79]
	v_mov_b32_e32 v80, v23
	v_mov_b32_e32 v81, v19
	s_waitcnt vmcnt(0)
	v_mov_b32_e32 v83, v1
	v_pk_fma_f32 v[78:79], v[80:81], v[80:81], v[78:79]
	v_mov_b32_e32 v80, v4
	v_mov_b32_e32 v81, v0
	v_pk_mul_f32 v[82:83], v[82:83], v[82:83]
	s_nop 0
	v_pk_fma_f32 v[80:81], v[80:81], v[80:81], v[82:83]
	v_mov_b32_e32 v82, v6
	v_mov_b32_e32 v83, v2
	v_pk_fma_f32 v[80:81], v[82:83], v[82:83], v[80:81]
	v_mov_b32_e32 v82, v7
	v_mov_b32_e32 v83, v3
	v_pk_fma_f32 v[80:81], v[82:83], v[82:83], v[80:81]
	v_mov_b32_e32 v82, v76
	v_mov_b32_e32 v83, v64
	v_mov_b32_e32 v64, v77
	v_pk_add_f32 v[64:65], v[82:83], v[64:65]
	v_mov_b32_e32 v76, v80
	v_mov_b32_e32 v77, v78
	v_pk_add_f32 v[64:65], v[64:65], v[76:77]
	v_mov_b32_e32 v78, v81
	v_pk_add_f32 v[64:65], v[64:65], v[78:79]
	ds_bpermute_b32 v77, v59, v65
	ds_bpermute_b32 v76, v59, v64
	s_waitcnt lgkmcnt(0)
	v_pk_add_f32 v[64:65], v[64:65], v[76:77]
	ds_bpermute_b32 v77, v66, v65
	ds_bpermute_b32 v76, v66, v64
	s_waitcnt lgkmcnt(0)
	v_pk_add_f32 v[64:65], v[64:65], v[76:77]
	ds_bpermute_b32 v77, v67, v65
	ds_bpermute_b32 v76, v67, v64
	s_waitcnt lgkmcnt(0)
	v_pk_add_f32 v[64:65], v[64:65], v[76:77]
	ds_bpermute_b32 v77, v68, v65
	ds_bpermute_b32 v76, v68, v64
	s_waitcnt lgkmcnt(0)
	v_pk_add_f32 v[64:65], v[64:65], v[76:77]
	ds_bpermute_b32 v77, v69, v65
	ds_bpermute_b32 v76, v69, v64
	s_waitcnt lgkmcnt(0)
	v_pk_add_f32 v[64:65], v[64:65], v[76:77]
	ds_bpermute_b32 v77, v70, v65
	ds_bpermute_b32 v76, v70, v64
	s_waitcnt lgkmcnt(0)
	v_pk_add_f32 v[64:65], v[64:65], v[76:77]
	global_load_dwordx4 v[76:79], v[32:33], off
	global_load_dwordx4 v[80:83], v[62:63], off
	global_load_dwordx4 v[84:87], v[50:51], off
	v_pk_fma_f32 v[64:65], v[64:65], s[52:53], v[142:143] op_sel_hi:[1,0,0]
	s_waitcnt vmcnt(1)
	v_pk_add_f32 v[92:93], v[80:81], 1.0 op_sel_hi:[1,0]
	v_mul_f32_e32 v54, 0x4b800000, v65
	v_cmp_gt_f32_e64 s[0:1], s15, v65
	v_pk_add_f32 v[94:95], v[82:83], 1.0 op_sel_hi:[1,0]
	v_cmp_gt_f32_e32 vcc, s15, v64
	v_cndmask_b32_e64 v54, v65, v54, s[0:1]
	v_rsq_f32_e32 v54, v54
	s_nop 0
	v_mul_f32_e32 v58, 0x45800000, v54
	v_cndmask_b32_e64 v58, v54, v58, s[0:1]
	v_pk_mul_f32 v[28:29], v[28:29], v[58:59] op_sel_hi:[1,0]
	v_pk_mul_f32 v[30:31], v[30:31], v[58:59] op_sel_hi:[1,0]
	v_pk_mul_f32 v[28:29], v[76:77], v[28:29]
	v_pk_mul_f32 v[30:31], v[78:79], v[30:31]
	s_waitcnt vmcnt(0)
; DI unsigned pack2(float lo, float hi) { f32x2_t v = {lo, hi}; bf16x2_t r = __builtin_convertvector(v, bf16x2_t); return __builtin_bit_cast(unsigned, r); }
; DI void phase_norm(const Params& p, int layer, int which  , int nrows) {
;     ...
; #pragma unroll
;     for (int i = 0; i < 4; ++i) {
;       ss0 += v[0][i].x * v[0][i].x + v[0][i].y * v[0][i].y + v[0][i].z * v[0][i].z + v[0][i].w * v[0][i].w;
;       ss1 += v[1][i].x * v[1][i].x + v[1][i].y * v[1][i].y + v[1][i].z * v[1][i].z + v[1][i].w * v[1][i].w;
;     }
;     ss0 = wave_sum(ss0); ss1 = wave_sum(ss1);
;     const float rstd0 = rsqrtf(ss0 * (1.0f / D) + 1e-6f), rstd1 = rsqrtf(ss1 * (1.0f / D) + 1e-6f);
; #pragma unroll
;     for (int k = 0; k < 2; ++k) {
;       const float rstd = k == 0 ? rstd0 : rstd1;
; #pragma unroll
;       for (int i = 0; i < 4; ++i) {
;         const int col = 4 * (lane + 64 * i);
;         float y0 = v[k][i].x * rstd * gg[i].x * (1.f + s4[i].x) + h4[i].x;
;         float y1 = v[k][i].y * rstd * gg[i].y * (1.f + s4[i].y) + h4[i].y;
;         float y2 = v[k][i].z * rstd * gg[i].z * (1.f + s4[i].z) + h4[i].z;
;         float y3 = v[k][i].w * rstd * gg[i].w * (1.f + s4[i].w) + h4[i].w;
;         uint2 w; w.x = pack2(y0, y1); w.y = pack2(y2, y3);
;         *(uint2*)(H + (size_t)(row + k) * D + col) = w;
;       }
;     }
	v_pk_fma_f32 v[28:29], v[92:93], v[28:29], v[84:85]
	v_pk_fma_f32 v[30:31], v[94:95], v[30:31], v[86:87]
	v_cvt_pk_bf16_f32 v96, v28, v29
	v_cvt_pk_bf16_f32 v97, v30, v31
	global_load_dwordx4 v[28:31], v[32:33], off offset:1024
	s_nop 0
	global_load_dwordx4 v[60:63], v[60:61], off
	s_nop 0
	global_load_dwordx4 v[80:83], v[50:51], off offset:1024
	v_pk_mul_f32 v[24:25], v[24:25], v[58:59] op_sel_hi:[1,0]
	v_pk_mul_f32 v[26:27], v[26:27], v[58:59] op_sel_hi:[1,0]
	v_pk_mul_f32 v[20:21], v[20:21], v[58:59] op_sel_hi:[1,0]
	v_pk_mul_f32 v[22:23], v[22:23], v[58:59] op_sel_hi:[1,0]
	v_mul_f32_e32 v54, 0x4b800000, v64
	v_cndmask_b32_e32 v54, v64, v54, vcc
	v_rsq_f32_e32 v54, v54
	v_pk_mul_f32 v[16:17], v[16:17], v[58:59] op_sel_hi:[1,0]
	v_pk_mul_f32 v[18:19], v[18:19], v[58:59] op_sel_hi:[1,0]
	v_mul_f32_e32 v64, 0x45800000, v54
	v_cndmask_b32_e32 v54, v54, v64, vcc
	v_lshlrev_b64 v[64:65], 11, v[36:37]
	v_pk_mul_f32 v[12:13], v[12:13], v[54:55] op_sel_hi:[1,0]
	v_pk_mul_f32 v[14:15], v[14:15], v[54:55] op_sel_hi:[1,0]
	v_pk_mul_f32 v[8:9], v[8:9], v[54:55] op_sel_hi:[1,0]
	v_pk_mul_f32 v[10:11], v[10:11], v[54:55] op_sel_hi:[1,0]
	v_pk_mul_f32 v[4:5], v[4:5], v[54:55] op_sel_hi:[1,0]
	v_pk_mul_f32 v[6:7], v[6:7], v[54:55] op_sel_hi:[1,0]
	v_pk_mul_f32 v[0:1], v[0:1], v[54:55] op_sel_hi:[1,0]
	v_pk_mul_f32 v[2:3], v[2:3], v[54:55] op_sel_hi:[1,0]
	v_lshl_add_u64 v[64:65], v[34:35], 0, v[64:65]
	v_pk_mul_f32 v[12:13], v[76:77], v[12:13]
	v_pk_mul_f32 v[14:15], v[78:79], v[14:15]
	v_add_u32_e32 v55, s53, v55
	v_pk_fma_f32 v[12:13], v[92:93], v[12:13], v[84:85]
	v_pk_fma_f32 v[14:15], v[94:95], v[14:15], v[86:87]
	v_cmp_lt_i32_e32 vcc, s95, v55
	v_cvt_pk_bf16_f32 v12, v12, v13
	v_cvt_pk_bf16_f32 v13, v14, v15
	v_add_u32_e32 v36, s54, v36
	s_or_b64 s[36:37], vcc, s[36:37]
	s_waitcnt vmcnt(2)
	v_pk_mul_f32 v[24:25], v[28:29], v[24:25]
	s_waitcnt vmcnt(1)
	v_pk_add_f32 v[98:99], v[60:61], 1.0 op_sel_hi:[1,0]
	v_pk_mul_f32 v[26:27], v[30:31], v[26:27]
	v_pk_add_f32 v[100:101], v[62:63], 1.0 op_sel_hi:[1,0]
	s_waitcnt vmcnt(0)
	v_pk_fma_f32 v[24:25], v[98:99], v[24:25], v[80:81]
	v_pk_fma_f32 v[26:27], v[100:101], v[26:27], v[82:83]
	v_cvt_pk_bf16_f32 v102, v24, v25
	v_cvt_pk_bf16_f32 v103, v26, v27
	global_load_dwordx4 v[24:27], v[32:33], off offset:2048
	global_load_dwordx4 v[60:63], v[56:57], off
	global_load_dwordx4 v[88:91], v[50:51], off offset:2048
	v_pk_mul_f32 v[8:9], v[28:29], v[8:9]
	v_pk_mul_f32 v[10:11], v[30:31], v[10:11]
	v_pk_fma_f32 v[8:9], v[98:99], v[8:9], v[80:81]
	v_pk_fma_f32 v[10:11], v[100:101], v[10:11], v[82:83]
	v_cvt_pk_bf16_f32 v8, v8, v9
	v_cvt_pk_bf16_f32 v9, v10, v11
	s_waitcnt vmcnt(2)
	v_pk_mul_f32 v[20:21], v[24:25], v[20:21]
	s_waitcnt vmcnt(1)
	v_pk_add_f32 v[56:57], v[60:61], 1.0 op_sel_hi:[1,0]
	v_pk_mul_f32 v[22:23], v[26:27], v[22:23]
	v_pk_add_f32 v[104:105], v[62:63], 1.0 op_sel_hi:[1,0]
	s_waitcnt vmcnt(0)
	v_pk_fma_f32 v[20:21], v[56:57], v[20:21], v[88:89]
	v_pk_fma_f32 v[22:23], v[104:105], v[22:23], v[90:91]
	v_cvt_pk_bf16_f32 v106, v20, v21
	v_cvt_pk_bf16_f32 v107, v22, v23
	global_load_dwordx4 v[20:23], v[32:33], off offset:3072
	global_load_dwordx4 v[60:63], v[52:53], off
	s_nop 0
	global_load_dwordx4 v[50:53], v[50:51], off offset:3072
	v_pk_mul_f32 v[4:5], v[24:25], v[4:5]
	v_pk_mul_f32 v[6:7], v[26:27], v[6:7]
	v_sub_u32_e32 v166, v64, v162
	v_lshrrev_b32_e32 v166, 5, v166
	v_lshl_add_u64 v[144:145], v[166:167], 0, v[160:161]
	v_lshl_add_u64 v[146:147], v[144:145], 0, v[164:165]
	v_lshl_add_u64 v[148:149], v[146:147], 0, v[164:165]
	v_lshl_add_u64 v[150:151], v[148:149], 0, v[164:165]
	global_store_dwordx2 v[144:145], v[96:97], off
	global_store_dwordx2 v[146:147], v[102:103], off
	global_store_dwordx2 v[148:149], v[106:107], off
	v_pk_fma_f32 v[4:5], v[56:57], v[4:5], v[88:89]
	v_pk_fma_f32 v[6:7], v[104:105], v[6:7], v[90:91]
	v_cvt_pk_bf16_f32 v4, v4, v5
	v_cvt_pk_bf16_f32 v5, v6, v7
	s_waitcnt vmcnt(5)
	v_pk_mul_f32 v[16:17], v[20:21], v[16:17]
	s_waitcnt vmcnt(4)
	v_pk_add_f32 v[60:61], v[60:61], 1.0 op_sel_hi:[1,0]
	v_pk_mul_f32 v[18:19], v[22:23], v[18:19]
	v_pk_add_f32 v[62:63], v[62:63], 1.0 op_sel_hi:[1,0]
	s_waitcnt vmcnt(3)
	v_pk_fma_f32 v[16:17], v[60:61], v[16:17], v[50:51]
	v_pk_fma_f32 v[18:19], v[62:63], v[18:19], v[52:53]
	v_cvt_pk_bf16_f32 v16, v16, v17
	v_cvt_pk_bf16_f32 v17, v18, v19
	v_pk_mul_f32 v[0:1], v[20:21], v[0:1]
	v_pk_mul_f32 v[2:3], v[22:23], v[2:3]
	global_store_dwordx2 v[150:151], v[16:17], off
	v_lshlrev_b64 v[16:17], 11, v[48:49]
	v_pk_fma_f32 v[0:1], v[60:61], v[0:1], v[50:51]
	v_pk_fma_f32 v[2:3], v[62:63], v[2:3], v[52:53]
	v_lshl_add_u64 v[14:15], v[34:35], 0, v[16:17]
	v_cvt_pk_bf16_f32 v0, v0, v1
	v_cvt_pk_bf16_f32 v1, v2, v3
	v_sub_u32_e32 v174, v14, v162
	v_lshrrev_b32_e32 v174, 5, v174
	v_lshl_add_u64 v[152:153], v[174:175], 0, v[160:161]
	v_lshl_add_u64 v[154:155], v[152:153], 0, v[164:165]
	v_lshl_add_u64 v[156:157], v[154:155], 0, v[164:165]
	v_lshl_add_u64 v[158:159], v[156:157], 0, v[164:165]
	global_store_dwordx2 v[152:153], v[12:13], off
	global_store_dwordx2 v[154:155], v[8:9], off
	global_store_dwordx2 v[156:157], v[4:5], off
	global_store_dwordx2 v[158:159], v[0:1], off
	s_andn2_b64 exec, exec, s[36:37]
	s_cbranch_execnz .LBB0_333

; DI void phase_norm(const Params& p, int layer, int which  , int nrows) {
;     ...
;   for (int pr = gw; pr < (nrows >> 1); pr += nw) {
;     const int row = pr * 2;
;     const float* xr0 = xold_ptr(p, layer, first, row);
;     const float* xr1 = xold_ptr(p, layer, first, row + 1);
;     const int b9 = row < NLAT ? (row >> 12) : 8;
;     float4 v[2][4];
;     float ss0 = 0.f, ss1 = 0.f;
; #pragma unroll
;     for (int i = 0; i < 4; ++i) {
;       typedef float f4ld __attribute__((ext_vector_type(4)));
;       const f4ld a_ = __builtin_nontemporal_load((const f4ld*)xr0 + lane + 64 * i), b_ = __builtin_nontemporal_load((const f4ld*)xr1 + lane + 64 * i);
;       v[0][i] = make_float4(a_[0], a_[1], a_[2], a_[3]); v[1][i] = make_float4(b_[0], b_[1], b_[2], b_[3]);
;     }
;     const float* sh = mod + b9 * 6144 + (which == 0 ? 0 : 3) * 1024;
;     const float* sc = sh + 1024;
;     float4 gg[4], s4[4], h4[4];
; #pragma unroll
;     for (int i = 0; i < 4; ++i) {
;       const int col = 4 * (lane + 64 * i);
;       gg[i] = *(const float4*)(g + col); s4[i] = *(const float4*)(sc + col); h4[i] = *(const float4*)(sh + col);
;     }
; #pragma unroll
;     for (int i = 0; i < 4; ++i) {
;       ss0 += v[0][i].x * v[0][i].x + v[0][i].y * v[0][i].y + v[0][i].z * v[0][i].z + v[0][i].w * v[0][i].w;
;       ss1 += v[1][i].x * v[1][i].x + v[1][i].y * v[1][i].y + v[1][i].z * v[1][i].z + v[1][i].w * v[1][i].w;
;     }
;     ss0 = wave_sum(ss0); ss1 = wave_sum(ss1);
;     const float rstd0 = rsqrtf(ss0 * (1.0f / D) + 1e-6f), rstd1 = rsqrtf(ss1 * (1.0f / D) + 1e-6f);
.LBB0_1596:
	v_cmp_gt_i32_e32 vcc, s29, v53
	v_add_u32_e32 v0, 0xffff8000, v36
	v_ashrrev_i32_e32 v37, 31, v36
	v_cndmask_b32_e32 v1, 0, v37, vcc
	v_cndmask_b32_e32 v0, v0, v36, vcc
	v_mov_b32_e32 v4, s14
	v_mov_b32_e32 v5, s23
	v_mov_b32_e32 v6, s35
	v_mov_b32_e32 v7, s22
	v_cndmask_b32_e32 v3, v4, v5, vcc
	v_cndmask_b32_e32 v2, v6, v7, vcc
	v_lshlrev_b64 v[0:1], 12, v[0:1]
	v_add_u32_e32 v46, 1, v36
	v_lshl_add_u64 v[0:1], v[2:3], 0, v[0:1]
	v_cmp_gt_i32_e32 vcc, s30, v46
	v_ashrrev_i32_e32 v2, 31, v46
	v_add_u32_e32 v3, 0xffff8001, v36
	v_cndmask_b32_e32 v47, 0, v2, vcc
	v_cndmask_b32_e32 v2, v3, v46, vcc
	v_mov_b32_e32 v3, v47
	v_cndmask_b32_e32 v5, v4, v5, vcc
	v_cndmask_b32_e32 v4, v6, v7, vcc
	v_lshlrev_b64 v[2:3], 12, v[2:3]
	v_lshl_add_u64 v[2:3], v[4:5], 0, v[2:3]
	v_lshl_add_u64 v[0:1], v[0:1], 0, v[140:141]
	v_lshl_add_u64 v[2:3], v[2:3], 0, v[140:141]
	global_load_dwordx4 v[28:31], v[0:1], off
	global_load_dwordx4 v[12:15], v[2:3], off
	global_load_dwordx4 v[24:27], v[0:1], off offset:1024
	global_load_dwordx4 v[8:11], v[2:3], off offset:1024
	global_load_dwordx4 v[20:23], v[0:1], off offset:2048
	global_load_dwordx4 v[4:7], v[2:3], off offset:2048
	global_load_dwordx4 v[16:19], v[0:1], off offset:3072
	s_nop 0
	global_load_dwordx4 v[0:3], v[2:3], off offset:3072
	v_min_i32_e32 v39, 0x4000, v53
	v_ashrrev_i32_e32 v39, 11, v39
	v_mul_i32_i24_e32 v48, 0x1800, v39
	v_ashrrev_i32_e32 v49, 31, v48
	v_lshl_add_u64 v[48:49], v[48:49], 2, s[12:13]
	v_lshl_add_u64 v[50:51], v[48:49], 0, s[38:39]
	v_mov_b32_e32 v39, v141
	v_lshl_add_u64 v[60:61], v[50:51], 0, v[38:39]
	v_lshl_add_u64 v[48:49], v[48:49], 0, v[38:39]
	v_mov_b32_e32 v41, v141
	v_lshl_add_u64 v[58:59], v[50:51], 0, v[40:41]
	v_mov_b32_e32 v43, v141
	v_lshl_add_u64 v[54:55], v[50:51], 0, v[42:43]
	v_mov_b32_e32 v45, v141
	v_lshl_add_u64 v[50:51], v[50:51], 0, v[44:45]
	s_waitcnt vmcnt(7)
	v_mov_b32_e32 v70, v29
	v_mov_b32_e32 v62, v28
	s_waitcnt vmcnt(5)
	v_mov_b32_e32 v71, v25
	v_mov_b32_e32 v63, v24
	v_pk_mul_f32 v[70:71], v[70:71], v[70:71]
	v_mov_b32_e32 v72, v13
	v_pk_fma_f32 v[62:63], v[62:63], v[62:63], v[70:71]
	v_mov_b32_e32 v70, v30
	v_mov_b32_e32 v71, v26
	v_pk_fma_f32 v[62:63], v[70:71], v[70:71], v[62:63]
	v_mov_b32_e32 v70, v31
	v_mov_b32_e32 v71, v27
	s_waitcnt vmcnt(4)
	v_mov_b32_e32 v73, v9
	v_pk_fma_f32 v[62:63], v[70:71], v[70:71], v[62:63]
	v_mov_b32_e32 v70, v12
	v_mov_b32_e32 v71, v8
	v_pk_mul_f32 v[72:73], v[72:73], v[72:73]
	s_waitcnt vmcnt(3)
	v_mov_b32_e32 v74, v21
	v_pk_fma_f32 v[70:71], v[70:71], v[70:71], v[72:73]
	v_mov_b32_e32 v72, v14
	v_mov_b32_e32 v73, v10
	v_pk_fma_f32 v[70:71], v[72:73], v[72:73], v[70:71]
	v_mov_b32_e32 v72, v15
	v_mov_b32_e32 v73, v11
	s_waitcnt vmcnt(1)
	v_mov_b32_e32 v75, v17
	v_pk_fma_f32 v[70:71], v[72:73], v[72:73], v[70:71]
	v_mov_b32_e32 v72, v20
	v_mov_b32_e32 v73, v16
	v_pk_mul_f32 v[74:75], v[74:75], v[74:75]
	v_mov_b32_e32 v76, v5
	v_pk_fma_f32 v[72:73], v[72:73], v[72:73], v[74:75]
	v_mov_b32_e32 v74, v22
	v_mov_b32_e32 v75, v18
	v_pk_fma_f32 v[72:73], v[74:75], v[74:75], v[72:73]
	v_mov_b32_e32 v74, v23
	v_mov_b32_e32 v75, v19
	s_waitcnt vmcnt(0)
	v_mov_b32_e32 v77, v1
	v_pk_fma_f32 v[72:73], v[74:75], v[74:75], v[72:73]
	v_mov_b32_e32 v74, v4
	v_mov_b32_e32 v75, v0
	v_pk_mul_f32 v[76:77], v[76:77], v[76:77]
	s_nop 0
	v_pk_fma_f32 v[74:75], v[74:75], v[74:75], v[76:77]
	v_mov_b32_e32 v76, v6
	v_mov_b32_e32 v77, v2
	v_pk_fma_f32 v[74:75], v[76:77], v[76:77], v[74:75]
	v_mov_b32_e32 v76, v7
	v_mov_b32_e32 v77, v3
	v_pk_fma_f32 v[74:75], v[76:77], v[76:77], v[74:75]
	v_mov_b32_e32 v76, v70
	v_mov_b32_e32 v77, v62
	v_mov_b32_e32 v62, v71
	v_pk_add_f32 v[62:63], v[76:77], v[62:63]
	v_mov_b32_e32 v70, v74
	v_mov_b32_e32 v71, v72
	v_pk_add_f32 v[62:63], v[62:63], v[70:71]
	v_mov_b32_e32 v72, v75
	v_pk_add_f32 v[62:63], v[62:63], v[72:73]
	ds_bpermute_b32 v71, v57, v63
	ds_bpermute_b32 v70, v57, v62
	s_waitcnt lgkmcnt(0)
	v_pk_add_f32 v[62:63], v[62:63], v[70:71]
	ds_bpermute_b32 v71, v64, v63
	ds_bpermute_b32 v70, v64, v62
	s_waitcnt lgkmcnt(0)
	v_pk_add_f32 v[62:63], v[62:63], v[70:71]
	ds_bpermute_b32 v71, v65, v63
	ds_bpermute_b32 v70, v65, v62
	s_waitcnt lgkmcnt(0)
	v_pk_add_f32 v[62:63], v[62:63], v[70:71]
	ds_bpermute_b32 v71, v66, v63
	ds_bpermute_b32 v70, v66, v62
	s_waitcnt lgkmcnt(0)
	v_pk_add_f32 v[62:63], v[62:63], v[70:71]
	ds_bpermute_b32 v71, v67, v63
	ds_bpermute_b32 v70, v67, v62
	s_waitcnt lgkmcnt(0)
	v_pk_add_f32 v[62:63], v[62:63], v[70:71]
	ds_bpermute_b32 v71, v68, v63
	ds_bpermute_b32 v70, v68, v62
	s_waitcnt lgkmcnt(0)
	v_pk_add_f32 v[62:63], v[62:63], v[70:71]
	global_load_dwordx4 v[70:73], v[32:33], off
	global_load_dwordx4 v[74:77], v[60:61], off
	global_load_dwordx4 v[78:81], v[48:49], off
	v_pk_fma_f32 v[62:63], v[62:63], s[40:41], v[142:143] op_sel_hi:[1,0,0]
	s_waitcnt vmcnt(1)
	v_pk_add_f32 v[86:87], v[74:75], 1.0 op_sel_hi:[1,0]
	v_mul_f32_e32 v39, 0x4b800000, v63
	v_cmp_gt_f32_e64 s[0:1], s15, v63
	v_pk_add_f32 v[88:89], v[76:77], 1.0 op_sel_hi:[1,0]
	v_cmp_gt_f32_e32 vcc, s15, v62
	v_cndmask_b32_e64 v39, v63, v39, s[0:1]
	v_rsq_f32_e32 v39, v39
	s_nop 0
	v_mul_f32_e32 v41, 0x45800000, v39
	v_cndmask_b32_e64 v56, v39, v41, s[0:1]
	v_pk_mul_f32 v[28:29], v[28:29], v[56:57] op_sel_hi:[1,0]
	v_pk_mul_f32 v[30:31], v[30:31], v[56:57] op_sel_hi:[1,0]
	v_pk_mul_f32 v[28:29], v[70:71], v[28:29]
	v_pk_mul_f32 v[30:31], v[72:73], v[30:31]
	s_waitcnt vmcnt(0)
; DI unsigned pack2(float lo, float hi) { f32x2_t v = {lo, hi}; bf16x2_t r = __builtin_convertvector(v, bf16x2_t); return __builtin_bit_cast(unsigned, r); }
; DI void phase_norm(const Params& p, int layer, int which  , int nrows) {
;     ...
; #pragma unroll
;     for (int i = 0; i < 4; ++i) {
;       ss0 += v[0][i].x * v[0][i].x + v[0][i].y * v[0][i].y + v[0][i].z * v[0][i].z + v[0][i].w * v[0][i].w;
;       ss1 += v[1][i].x * v[1][i].x + v[1][i].y * v[1][i].y + v[1][i].z * v[1][i].z + v[1][i].w * v[1][i].w;
;     }
;     ss0 = wave_sum(ss0); ss1 = wave_sum(ss1);
;     const float rstd0 = rsqrtf(ss0 * (1.0f / D) + 1e-6f), rstd1 = rsqrtf(ss1 * (1.0f / D) + 1e-6f);
; #pragma unroll
;     for (int k = 0; k < 2; ++k) {
;       const float rstd = k == 0 ? rstd0 : rstd1;
; #pragma unroll
;       for (int i = 0; i < 4; ++i) {
;         const int col = 4 * (lane + 64 * i);
;         float y0 = v[k][i].x * rstd * gg[i].x * (1.f + s4[i].x) + h4[i].x;
;         float y1 = v[k][i].y * rstd * gg[i].y * (1.f + s4[i].y) + h4[i].y;
;         float y2 = v[k][i].z * rstd * gg[i].z * (1.f + s4[i].z) + h4[i].z;
;         float y3 = v[k][i].w * rstd * gg[i].w * (1.f + s4[i].w) + h4[i].w;
;         uint2 w; w.x = pack2(y0, y1); w.y = pack2(y2, y3);
;         *(uint2*)(H + (size_t)(row + k) * D + col) = w;
;       }
;     }
	v_pk_fma_f32 v[28:29], v[86:87], v[28:29], v[78:79]
	v_pk_fma_f32 v[30:31], v[88:89], v[30:31], v[80:81]
	v_cvt_pk_bf16_f32 v90, v28, v29
	v_cvt_pk_bf16_f32 v91, v30, v31
	global_load_dwordx4 v[28:31], v[32:33], off offset:1024
	s_nop 0
	global_load_dwordx4 v[58:61], v[58:59], off
	s_nop 0
	global_load_dwordx4 v[74:77], v[48:49], off offset:1024
	v_pk_mul_f32 v[24:25], v[24:25], v[56:57] op_sel_hi:[1,0]
	v_pk_mul_f32 v[26:27], v[26:27], v[56:57] op_sel_hi:[1,0]
	v_pk_mul_f32 v[20:21], v[20:21], v[56:57] op_sel_hi:[1,0]
	v_pk_mul_f32 v[22:23], v[22:23], v[56:57] op_sel_hi:[1,0]
	v_mul_f32_e32 v39, 0x4b800000, v62
	v_cndmask_b32_e32 v39, v62, v39, vcc
	v_rsq_f32_e32 v39, v39
	v_pk_mul_f32 v[16:17], v[16:17], v[56:57] op_sel_hi:[1,0]
	v_pk_mul_f32 v[18:19], v[18:19], v[56:57] op_sel_hi:[1,0]
	v_lshlrev_b64 v[62:63], 11, v[36:37]
	v_mul_f32_e32 v41, 0x45800000, v39
	v_cndmask_b32_e32 v52, v39, v41, vcc
	v_pk_mul_f32 v[12:13], v[12:13], v[52:53] op_sel_hi:[1,0]
	v_pk_mul_f32 v[14:15], v[14:15], v[52:53] op_sel_hi:[1,0]
	v_pk_mul_f32 v[8:9], v[8:9], v[52:53] op_sel_hi:[1,0]
	v_pk_mul_f32 v[10:11], v[10:11], v[52:53] op_sel_hi:[1,0]
	v_pk_mul_f32 v[4:5], v[4:5], v[52:53] op_sel_hi:[1,0]
	v_pk_mul_f32 v[6:7], v[6:7], v[52:53] op_sel_hi:[1,0]
	v_pk_mul_f32 v[0:1], v[0:1], v[52:53] op_sel_hi:[1,0]
	v_pk_mul_f32 v[2:3], v[2:3], v[52:53] op_sel_hi:[1,0]
	v_lshl_add_u64 v[62:63], v[34:35], 0, v[62:63]
	v_pk_mul_f32 v[12:13], v[70:71], v[12:13]
	v_pk_mul_f32 v[14:15], v[72:73], v[14:15]
	v_add_u32_e32 v53, s53, v53
	v_pk_fma_f32 v[12:13], v[86:87], v[12:13], v[78:79]
	v_pk_fma_f32 v[14:15], v[88:89], v[14:15], v[80:81]
	v_cmp_le_i32_e32 vcc, s28, v53
	v_cvt_pk_bf16_f32 v12, v12, v13
	v_cvt_pk_bf16_f32 v13, v14, v15
	v_add_u32_e32 v36, s54, v36
	s_or_b64 s[36:37], vcc, s[36:37]
	s_waitcnt vmcnt(2)
	v_pk_mul_f32 v[24:25], v[28:29], v[24:25]
	s_waitcnt vmcnt(1)
	v_pk_add_f32 v[92:93], v[58:59], 1.0 op_sel_hi:[1,0]
	v_pk_mul_f32 v[26:27], v[30:31], v[26:27]
	v_pk_add_f32 v[94:95], v[60:61], 1.0 op_sel_hi:[1,0]
	s_waitcnt vmcnt(0)
	v_pk_fma_f32 v[24:25], v[92:93], v[24:25], v[74:75]
	v_pk_fma_f32 v[26:27], v[94:95], v[26:27], v[76:77]
	v_cvt_pk_bf16_f32 v96, v24, v25
	v_cvt_pk_bf16_f32 v97, v26, v27
	global_load_dwordx4 v[24:27], v[32:33], off offset:2048
	global_load_dwordx4 v[58:61], v[54:55], off
	global_load_dwordx4 v[82:85], v[48:49], off offset:2048
	v_pk_mul_f32 v[8:9], v[28:29], v[8:9]
	v_pk_mul_f32 v[10:11], v[30:31], v[10:11]
	v_pk_fma_f32 v[8:9], v[92:93], v[8:9], v[74:75]
	v_pk_fma_f32 v[10:11], v[94:95], v[10:11], v[76:77]
	v_cvt_pk_bf16_f32 v8, v8, v9
	v_cvt_pk_bf16_f32 v9, v10, v11
	s_waitcnt vmcnt(2)
	v_pk_mul_f32 v[20:21], v[24:25], v[20:21]
	s_waitcnt vmcnt(1)
	v_pk_add_f32 v[54:55], v[58:59], 1.0 op_sel_hi:[1,0]
	v_pk_mul_f32 v[22:23], v[26:27], v[22:23]
	v_pk_add_f32 v[98:99], v[60:61], 1.0 op_sel_hi:[1,0]
	s_waitcnt vmcnt(0)
	v_pk_fma_f32 v[20:21], v[54:55], v[20:21], v[82:83]
	v_pk_fma_f32 v[22:23], v[98:99], v[22:23], v[84:85]
	v_cvt_pk_bf16_f32 v100, v20, v21
	v_cvt_pk_bf16_f32 v101, v22, v23
	global_load_dwordx4 v[20:23], v[32:33], off offset:3072
	global_load_dwordx4 v[58:61], v[50:51], off
	s_nop 0
	global_load_dwordx4 v[48:51], v[48:49], off offset:3072
	v_pk_mul_f32 v[4:5], v[24:25], v[4:5]
	v_pk_mul_f32 v[6:7], v[26:27], v[6:7]
	v_sub_u32_e32 v166, v62, v162
	v_lshrrev_b32_e32 v166, 5, v166
	v_lshl_add_u64 v[144:145], v[166:167], 0, v[160:161]
	v_lshl_add_u64 v[146:147], v[144:145], 0, v[164:165]
	v_lshl_add_u64 v[148:149], v[146:147], 0, v[164:165]
	v_lshl_add_u64 v[150:151], v[148:149], 0, v[164:165]
	global_store_dwordx2 v[144:145], v[90:91], off
	global_store_dwordx2 v[146:147], v[96:97], off
	global_store_dwordx2 v[148:149], v[100:101], off
	v_pk_fma_f32 v[4:5], v[54:55], v[4:5], v[82:83]
	v_pk_fma_f32 v[6:7], v[98:99], v[6:7], v[84:85]
	v_cvt_pk_bf16_f32 v4, v4, v5
	v_cvt_pk_bf16_f32 v5, v6, v7
	s_waitcnt vmcnt(5)
	v_pk_mul_f32 v[16:17], v[20:21], v[16:17]
	s_waitcnt vmcnt(4)
	v_pk_add_f32 v[58:59], v[58:59], 1.0 op_sel_hi:[1,0]
	v_pk_mul_f32 v[18:19], v[22:23], v[18:19]
	v_pk_add_f32 v[60:61], v[60:61], 1.0 op_sel_hi:[1,0]
	s_waitcnt vmcnt(3)
	v_pk_fma_f32 v[16:17], v[58:59], v[16:17], v[48:49]
	v_pk_fma_f32 v[18:19], v[60:61], v[18:19], v[50:51]
	v_cvt_pk_bf16_f32 v16, v16, v17
	v_cvt_pk_bf16_f32 v17, v18, v19
	v_pk_mul_f32 v[0:1], v[20:21], v[0:1]
	v_pk_mul_f32 v[2:3], v[22:23], v[2:3]
	global_store_dwordx2 v[150:151], v[16:17], off
	v_lshlrev_b64 v[16:17], 11, v[46:47]
	v_pk_fma_f32 v[0:1], v[58:59], v[0:1], v[48:49]
	v_pk_fma_f32 v[2:3], v[60:61], v[2:3], v[50:51]
	v_lshl_add_u64 v[14:15], v[34:35], 0, v[16:17]
	v_cvt_pk_bf16_f32 v0, v0, v1
	v_cvt_pk_bf16_f32 v1, v2, v3
	v_sub_u32_e32 v174, v14, v162
	v_lshrrev_b32_e32 v174, 5, v174
	v_lshl_add_u64 v[152:153], v[174:175], 0, v[160:161]
	v_lshl_add_u64 v[154:155], v[152:153], 0, v[164:165]
	v_lshl_add_u64 v[156:157], v[154:155], 0, v[164:165]
	v_lshl_add_u64 v[158:159], v[156:157], 0, v[164:165]
	global_store_dwordx2 v[152:153], v[12:13], off
	global_store_dwordx2 v[154:155], v[8:9], off
	global_store_dwordx2 v[156:157], v[4:5], off
	global_store_dwordx2 v[158:159], v[0:1], off
	s_andn2_b64 exec, exec, s[36:37]
	s_cbranch_execnz .LBB0_1596
